# GEMM3 fused-LN epilogue hand-rewritten: batched slot and ln loads without per-store waits, x loads triple-buffered; adaLN GEMV loop keeps 32 loads in flight
# speedup vs baseline: 1.0097x; 1.0097x over previous
; DI void phase_adaln(const Params& p, float* mod, unsigned char* lds) {
;     ...
; #pragma unroll 8
;         for (int r = rg; r < 4096; r += 32) { const float w = p.w_ada[(size_t)r * 12288 + col]; a0 += sc[r] * w; a1 += sc[4096 + r] * w; a2 += sc[8192 + r] * w; }
.LBB0_30:
	v_add_co_u32_e32 v22, vcc, 0xffa00000, v8
	global_load_dword v24, v[8:9], off
	s_nop 0
	v_addc_co_u32_e32 v23, vcc, -1, v9, vcc
	v_add_co_u32_e32 v30, vcc, 0xffb80000, v8
	global_load_dword v22, v[22:23], off
	s_nop 0
	v_addc_co_u32_e32 v31, vcc, -1, v9, vcc
	v_add_co_u32_e32 v32, vcc, 0xffd00000, v8
	v_add_co_u32_e64 v26, s[8:9], s22, v8
	s_nop 0
	v_addc_co_u32_e32 v33, vcc, -1, v9, vcc
	global_load_dword v30, v[30:31], off
	s_nop 0
	global_load_dword v32, v[32:33], off
	v_addc_co_u32_e64 v27, s[8:9], 0, v9, s[8:9]
	v_add_co_u32_e32 v34, vcc, 0xffe80000, v8
	v_add_co_u32_e64 v28, s[8:9], s23, v8
	s_nop 0
	v_addc_co_u32_e32 v35, vcc, -1, v9, vcc
	v_addc_co_u32_e64 v29, s[8:9], 0, v9, s[8:9]
	v_add_co_u32_e32 v36, vcc, s24, v8
	global_load_dword v34, v[34:35], off
	s_nop 0
	global_load_dword v26, v[26:27], off
	s_nop 0
	global_load_dword v28, v[28:29], off
	v_addc_co_u32_e32 v37, vcc, 0, v9, vcc
	global_load_dword v36, v[36:37], off
	v_lshl_add_u64 v[8:9], v[8:9], 0, s[16:17]
	v_add_co_u32_e32 v100, vcc, 0xffa00000, v8
	global_load_dword v102, v[8:9], off
	s_nop 0
	v_addc_co_u32_e32 v101, vcc, -1, v9, vcc
	v_add_co_u32_e32 v108, vcc, 0xffb80000, v8
	global_load_dword v100, v[100:101], off
	s_nop 0
	v_addc_co_u32_e32 v109, vcc, -1, v9, vcc
	v_add_co_u32_e32 v110, vcc, 0xffd00000, v8
	v_add_co_u32_e64 v104, s[8:9], s22, v8
	s_nop 0
	v_addc_co_u32_e32 v111, vcc, -1, v9, vcc
	global_load_dword v108, v[108:109], off
	s_nop 0
	global_load_dword v110, v[110:111], off
	v_addc_co_u32_e64 v105, s[8:9], 0, v9, s[8:9]
	v_add_co_u32_e32 v112, vcc, 0xffe80000, v8
	v_add_co_u32_e64 v106, s[8:9], s23, v8
	s_nop 0
	v_addc_co_u32_e32 v113, vcc, -1, v9, vcc
	v_addc_co_u32_e64 v107, s[8:9], 0, v9, s[8:9]
	v_add_co_u32_e32 v114, vcc, s24, v8
	global_load_dword v112, v[112:113], off
	s_nop 0
	global_load_dword v104, v[104:105], off
	s_nop 0
	global_load_dword v106, v[106:107], off
	v_addc_co_u32_e32 v115, vcc, 0, v9, vcc
	global_load_dword v114, v[114:115], off
	v_lshl_add_u64 v[8:9], v[8:9], 0, s[16:17]
	v_add_co_u32_e32 v116, vcc, 0xffa00000, v8
	global_load_dword v118, v[8:9], off
	s_nop 0
	v_addc_co_u32_e32 v117, vcc, -1, v9, vcc
	v_add_co_u32_e32 v124, vcc, 0xffb80000, v8
	global_load_dword v116, v[116:117], off
	s_nop 0
	v_addc_co_u32_e32 v125, vcc, -1, v9, vcc
	v_add_co_u32_e32 v126, vcc, 0xffd00000, v8
	v_add_co_u32_e64 v120, s[8:9], s22, v8
	s_nop 0
	v_addc_co_u32_e32 v127, vcc, -1, v9, vcc
	global_load_dword v124, v[124:125], off
	s_nop 0
	global_load_dword v126, v[126:127], off
	v_addc_co_u32_e64 v121, s[8:9], 0, v9, s[8:9]
	v_add_co_u32_e32 v128, vcc, 0xffe80000, v8
	v_add_co_u32_e64 v122, s[8:9], s23, v8
	s_nop 0
	v_addc_co_u32_e32 v129, vcc, -1, v9, vcc
	v_addc_co_u32_e64 v123, s[8:9], 0, v9, s[8:9]
	v_add_co_u32_e32 v130, vcc, s24, v8
	global_load_dword v128, v[128:129], off
	s_nop 0
	global_load_dword v120, v[120:121], off
	s_nop 0
	global_load_dword v122, v[122:123], off
	v_addc_co_u32_e32 v131, vcc, 0, v9, vcc
	global_load_dword v130, v[130:131], off
	v_lshl_add_u64 v[8:9], v[8:9], 0, s[16:17]
	v_add_co_u32_e32 v132, vcc, 0xffa00000, v8
	global_load_dword v134, v[8:9], off
	s_nop 0
	v_addc_co_u32_e32 v133, vcc, -1, v9, vcc
	v_add_co_u32_e32 v140, vcc, 0xffb80000, v8
	global_load_dword v132, v[132:133], off
	s_nop 0
	v_addc_co_u32_e32 v141, vcc, -1, v9, vcc
	v_add_co_u32_e32 v142, vcc, 0xffd00000, v8
	v_add_co_u32_e64 v136, s[8:9], s22, v8
	s_nop 0
	v_addc_co_u32_e32 v143, vcc, -1, v9, vcc
	global_load_dword v140, v[140:141], off
	s_nop 0
	global_load_dword v142, v[142:143], off
	v_addc_co_u32_e64 v137, s[8:9], 0, v9, s[8:9]
	v_add_co_u32_e32 v144, vcc, 0xffe80000, v8
	v_add_co_u32_e64 v138, s[8:9], s23, v8
	s_nop 0
	v_addc_co_u32_e32 v145, vcc, -1, v9, vcc
	v_addc_co_u32_e64 v139, s[8:9], 0, v9, s[8:9]
	v_add_co_u32_e32 v146, vcc, s24, v8
	global_load_dword v144, v[144:145], off
	s_nop 0
	global_load_dword v136, v[136:137], off
	s_nop 0
	global_load_dword v138, v[138:139], off
	v_addc_co_u32_e32 v147, vcc, 0, v9, vcc
	global_load_dword v146, v[146:147], off
	v_lshl_add_u64 v[8:9], v[8:9], 0, s[16:17]
	ds_read2_b32 v[38:39], v10 offset1:32
	v_add_u32_e32 v11, 0x4000, v10
	v_add_u32_e32 v21, 0x8000, v10
	ds_read2_b32 v[40:41], v10 offset0:64 offset1:96
	ds_read2_b32 v[42:43], v10 offset0:128 offset1:160
	ds_read2_b32 v[44:45], v10 offset0:192 offset1:224
	ds_read2_b32 v[46:47], v11 offset1:32
	ds_read2_b32 v[48:49], v21 offset1:32
	ds_read2_b32 v[50:51], v11 offset0:64 offset1:96
	ds_read2_b32 v[52:53], v21 offset0:64 offset1:96
	ds_read2_b32 v[54:55], v11 offset0:128 offset1:160
	ds_read2_b32 v[56:57], v21 offset0:128 offset1:160
	ds_read2_b32 v[58:59], v11 offset0:192 offset1:224
	ds_read2_b32 v[60:61], v21 offset0:192 offset1:224
	s_waitcnt lgkmcnt(6)
	v_mov_b32_e32 v62, v48
	v_mov_b32_e32 v63, v46
	v_mov_b32_e32 v46, v49
	s_waitcnt lgkmcnt(4)
	v_mov_b32_e32 v48, v52
	v_mov_b32_e32 v49, v50
	v_mov_b32_e32 v50, v53
	s_waitcnt lgkmcnt(2)
	v_mov_b32_e32 v52, v56
	v_mov_b32_e32 v53, v54
	v_mov_b32_e32 v54, v57
	v_add_u32_e32 v5, 0x100, v5
	s_waitcnt lgkmcnt(0)
	v_mov_b32_e32 v56, v60
	v_mov_b32_e32 v57, v58
	v_cmp_lt_u32_e32 vcc, s25, v5
	v_mov_b32_e32 v58, v61
	v_add_u32_e32 v10, 0x400, v10
	s_or_b64 s[18:19], vcc, s[18:19]
	s_waitcnt vmcnt(30)
	v_fmac_f32_e32 v3, v22, v38
	v_pk_fma_f32 v[6:7], v[22:23], v[62:63], v[6:7] op_sel_hi:[0,1,1]
	s_waitcnt vmcnt(29)
	v_fmac_f32_e32 v3, v30, v39
	v_pk_fma_f32 v[6:7], v[30:31], v[46:47], v[6:7] op_sel_hi:[0,1,1]
	s_waitcnt vmcnt(28)
	v_fmac_f32_e32 v3, v32, v40
	v_pk_fma_f32 v[6:7], v[32:33], v[48:49], v[6:7] op_sel_hi:[0,1,1]
	s_waitcnt vmcnt(27)
; DI void phase_adaln(const Params& p, float* mod, unsigned char* lds) {
;     ...
; #pragma unroll 8
;         for (int r = rg; r < 4096; r += 32) { const float w = p.w_ada[(size_t)r * 12288 + col]; a0 += sc[r] * w; a1 += sc[4096 + r] * w; a2 += sc[8192 + r] * w; }
	v_fmac_f32_e32 v3, v34, v41
	v_pk_fma_f32 v[6:7], v[34:35], v[50:51], v[6:7] op_sel_hi:[0,1,1]
	v_fmac_f32_e32 v3, v24, v42
	v_pk_fma_f32 v[6:7], v[24:25], v[52:53], v[6:7] op_sel_hi:[0,1,1]
	s_waitcnt vmcnt(26)
	v_fmac_f32_e32 v3, v26, v43
	v_pk_fma_f32 v[6:7], v[26:27], v[54:55], v[6:7] op_sel_hi:[0,1,1]
	s_waitcnt vmcnt(25)
	v_fmac_f32_e32 v3, v28, v44
	v_pk_fma_f32 v[6:7], v[28:29], v[56:57], v[6:7] op_sel_hi:[0,1,1]
	s_waitcnt vmcnt(24)
	v_fmac_f32_e32 v3, v36, v45
	v_pk_fma_f32 v[6:7], v[36:37], v[58:59], v[6:7] op_sel_hi:[0,1,1]
	ds_read2_b32 v[38:39], v10 offset1:32
	v_add_u32_e32 v11, 0x4000, v10
	v_add_u32_e32 v21, 0x8000, v10
	ds_read2_b32 v[40:41], v10 offset0:64 offset1:96
	ds_read2_b32 v[42:43], v10 offset0:128 offset1:160
	ds_read2_b32 v[44:45], v10 offset0:192 offset1:224
	ds_read2_b32 v[46:47], v11 offset1:32
	ds_read2_b32 v[48:49], v21 offset1:32
	ds_read2_b32 v[50:51], v11 offset0:64 offset1:96
	ds_read2_b32 v[52:53], v21 offset0:64 offset1:96
	ds_read2_b32 v[54:55], v11 offset0:128 offset1:160
	ds_read2_b32 v[56:57], v21 offset0:128 offset1:160
	ds_read2_b32 v[58:59], v11 offset0:192 offset1:224
	ds_read2_b32 v[60:61], v21 offset0:192 offset1:224
	s_waitcnt lgkmcnt(6)
	v_mov_b32_e32 v62, v48
	v_mov_b32_e32 v63, v46
	v_mov_b32_e32 v46, v49
	s_waitcnt lgkmcnt(4)
	v_mov_b32_e32 v48, v52
	v_mov_b32_e32 v49, v50
	v_mov_b32_e32 v50, v53
	s_waitcnt lgkmcnt(2)
	v_mov_b32_e32 v52, v56
	v_mov_b32_e32 v53, v54
	v_mov_b32_e32 v54, v57
	v_add_u32_e32 v5, 0x100, v5
	s_waitcnt lgkmcnt(0)
	v_mov_b32_e32 v56, v60
	v_mov_b32_e32 v57, v58
	v_cmp_lt_u32_e32 vcc, s25, v5
	v_mov_b32_e32 v58, v61
	v_add_u32_e32 v10, 0x400, v10
	s_or_b64 s[18:19], vcc, s[18:19]
	s_waitcnt vmcnt(22)
	v_fmac_f32_e32 v3, v100, v38
	v_pk_fma_f32 v[6:7], v[100:101], v[62:63], v[6:7] op_sel_hi:[0,1,1]
	s_waitcnt vmcnt(21)
	v_fmac_f32_e32 v3, v108, v39
	v_pk_fma_f32 v[6:7], v[108:109], v[46:47], v[6:7] op_sel_hi:[0,1,1]
	s_waitcnt vmcnt(20)
	v_fmac_f32_e32 v3, v110, v40
	v_pk_fma_f32 v[6:7], v[110:111], v[48:49], v[6:7] op_sel_hi:[0,1,1]
	s_waitcnt vmcnt(19)
	v_fmac_f32_e32 v3, v112, v41
	v_pk_fma_f32 v[6:7], v[112:113], v[50:51], v[6:7] op_sel_hi:[0,1,1]
	v_fmac_f32_e32 v3, v102, v42
	v_pk_fma_f32 v[6:7], v[102:103], v[52:53], v[6:7] op_sel_hi:[0,1,1]
	s_waitcnt vmcnt(18)
	v_fmac_f32_e32 v3, v104, v43
	v_pk_fma_f32 v[6:7], v[104:105], v[54:55], v[6:7] op_sel_hi:[0,1,1]
	s_waitcnt vmcnt(17)
	v_fmac_f32_e32 v3, v106, v44
	v_pk_fma_f32 v[6:7], v[106:107], v[56:57], v[6:7] op_sel_hi:[0,1,1]
	s_waitcnt vmcnt(16)
	v_fmac_f32_e32 v3, v114, v45
	v_pk_fma_f32 v[6:7], v[114:115], v[58:59], v[6:7] op_sel_hi:[0,1,1]
	ds_read2_b32 v[38:39], v10 offset1:32
	v_add_u32_e32 v11, 0x4000, v10
	v_add_u32_e32 v21, 0x8000, v10
	ds_read2_b32 v[40:41], v10 offset0:64 offset1:96
	ds_read2_b32 v[42:43], v10 offset0:128 offset1:160
	ds_read2_b32 v[44:45], v10 offset0:192 offset1:224
	ds_read2_b32 v[46:47], v11 offset1:32
	ds_read2_b32 v[48:49], v21 offset1:32
	ds_read2_b32 v[50:51], v11 offset0:64 offset1:96
	ds_read2_b32 v[52:53], v21 offset0:64 offset1:96
	ds_read2_b32 v[54:55], v11 offset0:128 offset1:160
	ds_read2_b32 v[56:57], v21 offset0:128 offset1:160
	ds_read2_b32 v[58:59], v11 offset0:192 offset1:224
	ds_read2_b32 v[60:61], v21 offset0:192 offset1:224
	s_waitcnt lgkmcnt(6)
	v_mov_b32_e32 v62, v48
	v_mov_b32_e32 v63, v46
	v_mov_b32_e32 v46, v49
	s_waitcnt lgkmcnt(4)
	v_mov_b32_e32 v48, v52
	v_mov_b32_e32 v49, v50
	v_mov_b32_e32 v50, v53
	s_waitcnt lgkmcnt(2)
	v_mov_b32_e32 v52, v56
	v_mov_b32_e32 v53, v54
	v_mov_b32_e32 v54, v57
	v_add_u32_e32 v5, 0x100, v5
	s_waitcnt lgkmcnt(0)
	v_mov_b32_e32 v56, v60
	v_mov_b32_e32 v57, v58
	v_cmp_lt_u32_e32 vcc, s25, v5
	v_mov_b32_e32 v58, v61
	v_add_u32_e32 v10, 0x400, v10
	s_or_b64 s[18:19], vcc, s[18:19]
	s_waitcnt vmcnt(14)
	v_fmac_f32_e32 v3, v116, v38
	v_pk_fma_f32 v[6:7], v[116:117], v[62:63], v[6:7] op_sel_hi:[0,1,1]
	s_waitcnt vmcnt(13)
	v_fmac_f32_e32 v3, v124, v39
	v_pk_fma_f32 v[6:7], v[124:125], v[46:47], v[6:7] op_sel_hi:[0,1,1]
	s_waitcnt vmcnt(12)
	v_fmac_f32_e32 v3, v126, v40
	v_pk_fma_f32 v[6:7], v[126:127], v[48:49], v[6:7] op_sel_hi:[0,1,1]
	s_waitcnt vmcnt(11)
	v_fmac_f32_e32 v3, v128, v41
	v_pk_fma_f32 v[6:7], v[128:129], v[50:51], v[6:7] op_sel_hi:[0,1,1]
	v_fmac_f32_e32 v3, v118, v42
	v_pk_fma_f32 v[6:7], v[118:119], v[52:53], v[6:7] op_sel_hi:[0,1,1]
	s_waitcnt vmcnt(10)
	v_fmac_f32_e32 v3, v120, v43
	v_pk_fma_f32 v[6:7], v[120:121], v[54:55], v[6:7] op_sel_hi:[0,1,1]
	s_waitcnt vmcnt(9)
	v_fmac_f32_e32 v3, v122, v44
	v_pk_fma_f32 v[6:7], v[122:123], v[56:57], v[6:7] op_sel_hi:[0,1,1]
	s_waitcnt vmcnt(8)
	v_fmac_f32_e32 v3, v130, v45
	v_pk_fma_f32 v[6:7], v[130:131], v[58:59], v[6:7] op_sel_hi:[0,1,1]
	ds_read2_b32 v[38:39], v10 offset1:32
	v_add_u32_e32 v11, 0x4000, v10
	v_add_u32_e32 v21, 0x8000, v10
	ds_read2_b32 v[40:41], v10 offset0:64 offset1:96
	ds_read2_b32 v[42:43], v10 offset0:128 offset1:160
	ds_read2_b32 v[44:45], v10 offset0:192 offset1:224
	ds_read2_b32 v[46:47], v11 offset1:32
	ds_read2_b32 v[48:49], v21 offset1:32
	ds_read2_b32 v[50:51], v11 offset0:64 offset1:96
	ds_read2_b32 v[52:53], v21 offset0:64 offset1:96
	ds_read2_b32 v[54:55], v11 offset0:128 offset1:160
	ds_read2_b32 v[56:57], v21 offset0:128 offset1:160
	ds_read2_b32 v[58:59], v11 offset0:192 offset1:224
	ds_read2_b32 v[60:61], v21 offset0:192 offset1:224
	s_waitcnt lgkmcnt(6)
	v_mov_b32_e32 v62, v48
	v_mov_b32_e32 v63, v46
	v_mov_b32_e32 v46, v49
	s_waitcnt lgkmcnt(4)
	v_mov_b32_e32 v48, v52
	v_mov_b32_e32 v49, v50
	v_mov_b32_e32 v50, v53
	s_waitcnt lgkmcnt(2)
	v_mov_b32_e32 v52, v56
	v_mov_b32_e32 v53, v54
	v_mov_b32_e32 v54, v57
	v_add_u32_e32 v5, 0x100, v5
	s_waitcnt lgkmcnt(0)
	v_mov_b32_e32 v56, v60
	v_mov_b32_e32 v57, v58
	v_cmp_lt_u32_e32 vcc, s25, v5
	v_mov_b32_e32 v58, v61
	v_add_u32_e32 v10, 0x400, v10
	s_or_b64 s[18:19], vcc, s[18:19]
	s_waitcnt vmcnt(6)
	v_fmac_f32_e32 v3, v132, v38
	v_pk_fma_f32 v[6:7], v[132:133], v[62:63], v[6:7] op_sel_hi:[0,1,1]
	s_waitcnt vmcnt(5)
	v_fmac_f32_e32 v3, v140, v39
	v_pk_fma_f32 v[6:7], v[140:141], v[46:47], v[6:7] op_sel_hi:[0,1,1]
	s_waitcnt vmcnt(4)
	v_fmac_f32_e32 v3, v142, v40
	v_pk_fma_f32 v[6:7], v[142:143], v[48:49], v[6:7] op_sel_hi:[0,1,1]
	s_waitcnt vmcnt(3)
	v_fmac_f32_e32 v3, v144, v41
	v_pk_fma_f32 v[6:7], v[144:145], v[50:51], v[6:7] op_sel_hi:[0,1,1]
	v_fmac_f32_e32 v3, v134, v42
	v_pk_fma_f32 v[6:7], v[134:135], v[52:53], v[6:7] op_sel_hi:[0,1,1]
	s_waitcnt vmcnt(2)
	v_fmac_f32_e32 v3, v136, v43
	v_pk_fma_f32 v[6:7], v[136:137], v[54:55], v[6:7] op_sel_hi:[0,1,1]
	s_waitcnt vmcnt(1)
	v_fmac_f32_e32 v3, v138, v44
	v_pk_fma_f32 v[6:7], v[138:139], v[56:57], v[6:7] op_sel_hi:[0,1,1]
	s_waitcnt vmcnt(0)
	v_fmac_f32_e32 v3, v146, v45
	v_pk_fma_f32 v[6:7], v[146:147], v[58:59], v[6:7] op_sel_hi:[0,1,1]
	s_andn2_b64 exec, exec, s[18:19]
	s_cbranch_execnz .LBB0_30
; DI void phase_adaln(const Params& p, float* mod, unsigned char* lds) {
;     ...
;         red[(rg * 3 + 0) * 16 + cc] = a0; red[(rg * 3 + 1) * 16 + cc] = a1; red[(rg * 3 + 2) * 16 + cc] = a2;
;         __syncthreads();
;         if (tid < 48) { const int cnd = tid >> 4, c2 = tid & 15; float s2 = 0.f;
;             for (int g = 0; g < 32; ++g) s2 += red[(g * 3 + cnd) * 16 + c2];
;             mod[cnd * 12288 + item * 16 + c2] = s2 + p.b_ada[item * 16 + c2]; }
	s_or_b64 exec, exec, s[18:19]
	v_add_u32_e32 v5, 0xc000, v15
	ds_write2_b32 v5, v3, v7 offset1:16
	ds_write_b32 v15, v6 offset:49280
	s_waitcnt lgkmcnt(0)
	s_barrier
	s_and_saveexec_b64 s[8:9], s[6:7]
	s_cbranch_execz .LBB0_24
	s_lshl_b32 s18, s26, 4
	v_or_b32_e32 v6, s18, v13
	v_ashrrev_i32_e32 v7, 31, v6
	v_lshl_add_u64 v[6:7], v[6:7], 2, s[66:67]
	global_load_dword v3, v[6:7], off
	v_add_u32_e32 v5, 0xc000, v20
	v_add_u32_e32 v26, 0xc600, v20
	v_add_u32_e32 v30, 0xc800, v20
	v_add_u32_e32 v36, 0xcc00, v20
	v_add_u32_e32 v40, 0xd000, v20
	v_add_u32_e32 v42, 0xd200, v20
	v_add_u32_e32 v46, 0xd400, v20
	v_add_u32_e32 v21, 0xc400, v20
	ds_read2_b32 v[6:7], v5 offset1:48
	ds_read2_b32 v[8:9], v5 offset0:96 offset1:144
	ds_read2_b32 v[10:11], v5 offset0:192 offset1:240
	ds_read2_b32 v[22:23], v21 offset0:32 offset1:80
	ds_read2_b32 v[24:25], v21 offset0:128 offset1:176
	ds_read2_b32 v[26:27], v26 offset0:96 offset1:144
	ds_read2_b32 v[28:29], v30 offset0:64 offset1:112
	ds_read2_b32 v[30:31], v30 offset0:160 offset1:208
	ds_read2_b32 v[32:33], v36 offset1:48
	ds_read2_b32 v[34:35], v36 offset0:96 offset1:144
	ds_read2_b32 v[36:37], v36 offset0:192 offset1:240
	ds_read2_b32 v[38:39], v40 offset0:32 offset1:80
	ds_read2_b32 v[40:41], v40 offset0:128 offset1:176
	ds_read2_b32 v[42:43], v42 offset0:96 offset1:144
	ds_read2_b32 v[44:45], v46 offset0:64 offset1:112
	ds_read2_b32 v[46:47], v46 offset0:160 offset1:208
	s_waitcnt lgkmcnt(14)
	v_add_f32_e32 v5, 0, v6
	v_add_f32_e32 v5, v5, v7
	v_add_f32_e32 v5, v5, v8
	v_add_f32_e32 v5, v5, v9
	s_waitcnt lgkmcnt(13)
	v_add_f32_e32 v5, v5, v10
	v_add_f32_e32 v5, v5, v11
	s_waitcnt lgkmcnt(12)
	v_add_f32_e32 v5, v5, v22
	v_add_f32_e32 v5, v5, v23
	s_waitcnt lgkmcnt(11)
	v_add_f32_e32 v5, v5, v24
	v_add_f32_e32 v5, v5, v25
	s_waitcnt lgkmcnt(10)
	v_add_f32_e32 v5, v5, v26
	v_add_f32_e32 v5, v5, v27
	s_waitcnt lgkmcnt(9)
	v_add_f32_e32 v5, v5, v28
	v_add_f32_e32 v5, v5, v29
	s_waitcnt lgkmcnt(8)
	v_add_f32_e32 v5, v5, v30
	v_add_f32_e32 v5, v5, v31
	s_waitcnt lgkmcnt(7)
	v_add_f32_e32 v5, v5, v32
	v_add_f32_e32 v5, v5, v33
	s_waitcnt lgkmcnt(6)
	v_add_f32_e32 v5, v5, v34
	v_add_f32_e32 v5, v5, v35
	s_waitcnt lgkmcnt(5)
	v_add_f32_e32 v5, v5, v36
	v_add_f32_e32 v5, v5, v37
	s_waitcnt lgkmcnt(4)
	v_add_f32_e32 v5, v5, v38
	v_add_f32_e32 v5, v5, v39
	s_waitcnt lgkmcnt(3)
	v_add_f32_e32 v5, v5, v40
	v_add_f32_e32 v5, v5, v41
	s_waitcnt lgkmcnt(2)
	v_add_f32_e32 v5, v5, v42
	v_add_f32_e32 v5, v5, v43
	s_waitcnt lgkmcnt(1)
	v_add_f32_e32 v5, v5, v44
	v_add_f32_e32 v5, v5, v45
	v_add_u32_e32 v48, s18, v16
	s_waitcnt lgkmcnt(0)
	v_add_f32_e32 v5, v5, v46
	v_ashrrev_i32_e32 v49, 31, v48
	v_add_f32_e32 v5, v5, v47
	v_lshl_add_u64 v[6:7], v[48:49], 2, s[80:81]
	s_waitcnt vmcnt(0)
	v_add_f32_e32 v3, v5, v3
	global_store_dword v[6:7], v3, off
	s_branch .LBB0_24

; #define LAS __attribute__((address_space(3)))
; DI float bflo(unsigned w) { return __uint_as_float(w << 16); }
; DI void hgrn_h2(const Params& p, int it, unsigned char* lds) {
;     ...
;     for (int n = 0; n < 132; ++n) {
;         const int cur = n & 1;
;         const bf16_t* Bc = L + cur * 20480;
;         const bf16_t* KutS = Bc; const bf16_t* QcS = Bc + 9216;
;         const unsigned vqb = (unsigned)(cur * 40960 + (9216 + 8704) * 2);
;         const bf16_t* Sc = Stb + cur * 4352; bf16_t* Sn = Stb + (cur ^ 1) * 4352;
;         f32x4 u[2];
; #pragma unroll
;         for (int q2 = 0; q2 < 2; ++q2) { const int db = (w >> 1) * 2 + q2; u[q2] = (f32x4){0.f, 0.f, 0.f, 0.f};
; #pragma unroll
;             for (int ks = 0; ks < 2; ++ks) {
;                 const s16x4 lo = __builtin_amdgcn_ds_read_tr16_b64_v4i16((LAS s16x4*)(l3 + vqb + (32 * ks + 8 * g + trq) * 80 + 32 * vb + 8 * trp));
;                 const s16x4 hi = __builtin_amdgcn_ds_read_tr16_b64_v4i16((LAS s16x4*)(l3 + vqb + (32 * ks + 8 * g + 4 + trq) * 80 + 32 * vb + 8 * trp));
;                 const bf16x8 fb = *(const bf16x8*)(KutS + (db * 16 + c16) * 72 + ks * 32 + g * 8);
;                 u[q2] = MFMA16(__builtin_shufflevector(lo, hi, 0, 1, 2, 3, 4, 5, 6, 7), fb, u[q2]); } }
;         if (n >= 4) {
;             f32x4 oacc = (f32x4){0.f, 0.f, 0.f, 0.f};
; #pragma unroll
;             for (int ks = 0; ks < 4; ++ks) { const bf16x8 fa = *(const bf16x8*)(QcS + (ib * 16 + c16) * 136 + ks * 32 + g * 8), fb = *(const bf16x8*)(Sc + (vb * 16 + c16) * 136 + ks * 32 + g * 8);
;                 oacc = MFMA16(fb, fa, oacc); }
;             int r0, sg; HG_ROW0(n, b, dir, r0, sg);
;             u32x2 ow; ow.x = cvt_pk_bf16(bflo(oinc.x) + oacc[0], bfhi(oinc.x) + oacc[1]); ow.y = cvt_pk_bf16(bflo(oinc.y) + oacc[2], bfhi(oinc.y) + oacc[3]);
;             *(u32x2*)(O + oix(dir, r0 + sg * (ib * 16 + c16), h, dvq * 32 + vb * 16 + 4 * g)) = ow;
;         }
; #pragma unroll
;         for (int q2 = 0; q2 < 2; ++q2) { const int db = (w >> 1) * 2 + q2;
;             Sreg[q2] = Sreg[q2] * decc[q2] + u[q2];
; #pragma unroll
;             for (int j = 0; j < 4; ++j) Sn[(vb * 16 + g * 4 + j) * 136 + db * 16 + c16] = f2bf(Sreg[q2][j]); }
;         if (n + 1 < 132) { H2_WRITE(cur ^ 1);
; #pragma unroll
;             for (int j = 0; j < 2; ++j) decc[j] = decr[j];
;             oinc = oinr; }
.LBB0_542:
	s_or_b64 exec, exec, s[12:13]
	s_lshl_b64 s[10:11], s[10:11], 9
	v_mul_i32_i24_e32 v104, s30, v78
	v_lshl_add_u64 v[12:13], v[32:33], 0, s[10:11]
	s_add_i32 s10, s14, 1
	s_ashr_i32 s11, s10, 31
	v_add_u32_e32 v18, s15, v104
	s_lshl_b64 s[10:11], s[10:11], 14
	v_ashrrev_i32_e32 v19, 31, v18
	v_lshl_add_u64 v[16:17], v[30:31], 0, s[10:11]
	v_mov_b32_e32 v37, v21
	v_lshl_add_u64 v[18:19], v[18:19], 0, s[8:9]
	v_lshl_add_u64 v[14:15], v[16:17], 0, v[36:37]
	v_mov_b32_e32 v39, v21
	v_lshlrev_b64 v[18:19], 8, v[18:19]
	global_load_dword v60, v[12:13], off offset:2560
	global_load_dword v58, v[12:13], off offset:2624
	s_nop 0
	global_load_dwordx4 v[12:15], v[14:15], off
	v_lshl_add_u64 v[16:17], v[16:17], 0, v[38:39]
	v_lshl_add_u64 v[66:67], v[44:45], 0, v[18:19]
	global_load_dwordx4 v[16:19], v[16:17], off
	s_nop 0
	global_load_dwordx2 v[66:67], v[66:67], off
	s_lshl_b32 s10, s27, 7
	s_lshl_b32 s11, s28, 11
	s_or_b32 s10, s11, s10
	s_or_b32 s12, s10, 2
	s_add_i32 s10, s29, s26
	s_add_i32 s10, s10, s27
	s_mul_i32 s15, s10, 0x84
	v_cndmask_b32_e64 v103, v91, v78, s[4:5]
	s_add_i32 s13, s31, 0x1f7f
	s_add_i32 s14, s12, s34
	s_add_i32 s15, s15, 6
	s_mov_b32 s16, 0
	s_mov_b32 s17, s31
	s_waitcnt lgkmcnt(0)
	s_barrier
.LBB0_543:
	s_add_i32 s26, s16, 4
	s_and_b32 s10, s26, 1
	s_mul_i32 s11, s10, 0xa000
	s_add_i32 s11, s11, 0
	v_add_u32_e32 v35, s11, v82
	v_lshl_add_u32 v37, v75, 1, s11
	v_add3_u32 v35, v35, v76, v201
	v_add_u32_e32 v39, v37, v83
	ds_read_b64_tr_b16 v[110:111], v35 offset:35840
	ds_read_b64_tr_b16 v[112:113], v35 offset:36160
	ds_read_b128 v[114:117], v39
	ds_read_b64_tr_b16 v[118:119], v35 offset:38400
	ds_read_b64_tr_b16 v[120:121], v35 offset:38720
	ds_read_b128 v[122:125], v39 offset:64
	v_add_u32_e32 v105, v37, v84
	s_waitcnt lgkmcnt(3)
	v_mfma_f32_16x16x32_bf16 v[114:117], v[110:113], v[114:117], 0
	ds_read_b128 v[126:129], v105
	ds_read_b128 v[130:133], v105 offset:64
	s_mul_i32 s11, s10, 0x2200
	v_add_u32_e32 v35, s11, v80
	s_waitcnt lgkmcnt(2)
	v_mfma_f32_16x16x32_bf16 v[114:117], v[118:121], v[122:125], v[114:117]
	ds_read_b128 v[122:125], v35
	v_add_u32_e32 v37, v37, v79
	s_waitcnt vmcnt(7)
	v_mov_b64_e32 v[138:139], v[48:49]
	s_waitcnt lgkmcnt(2)
	v_mfma_f32_16x16x32_bf16 v[110:113], v[110:113], v[126:129], 0
	s_waitcnt vmcnt(0)
	v_mov_b64_e32 v[48:49], v[66:67]
	s_xor_b32 s27, s10, 1
	s_mul_i32 s28, s27, 0x2200
	s_waitcnt lgkmcnt(1)
	v_mfma_f32_16x16x32_bf16 v[110:113], v[118:121], v[130:133], v[110:113]
	ds_read_b128 v[118:121], v35 offset:64
	ds_read_b128 v[126:129], v37 offset:18432
	ds_read_b128 v[130:133], v37 offset:18496
	v_pk_fma_f32 v[54:55], v[64:65], v[54:55], v[114:115] op_sel_hi:[0,1,1]
	v_pk_fma_f32 v[50:51], v[64:65], v[50:51], v[116:117] op_sel_hi:[0,1,1]
	s_waitcnt lgkmcnt(1)
	v_mfma_f32_16x16x32_bf16 v[122:125], v[122:125], v[126:129], 0
	ds_read_b128 v[126:129], v35 offset:128
	v_pk_fma_f32 v[56:57], v[62:63], v[56:57], v[110:111] op_sel_hi:[0,1,1]
	v_pk_fma_f32 v[52:53], v[62:63], v[52:53], v[112:113] op_sel_hi:[0,1,1]
	s_waitcnt lgkmcnt(1)
	v_mfma_f32_16x16x32_bf16 v[118:121], v[118:121], v[130:133], v[122:125]
	s_nop 2
	ds_read_b128 v[122:125], v37 offset:18560
	ds_read_b128 v[130:133], v35 offset:192
	ds_read_b128 v[134:137], v37 offset:18624
	v_lshlrev_b32_e32 v35, 16, v138
	s_waitcnt lgkmcnt(2)
	v_mfma_f32_16x16x32_bf16 v[118:121], v[126:129], v[122:125], v[118:121]
	v_and_b32_e32 v37, 0xffff0000, v138
	s_add_i32 s29, s13, 0x80
	s_and_b64 s[10:11], s[4:5], exec
	s_waitcnt lgkmcnt(0)
	v_mfma_f32_16x16x32_bf16 v[118:121], v[130:133], v[134:137], v[118:121]
	s_cselect_b32 s10, s17, s29
	s_mul_i32 s27, s27, 0xa000
	s_add_i32 s27, s27, 0
	s_nop 4
	v_add_f32_e32 v35, v118, v35
	v_add_f32_e32 v37, v119, v37
	v_cvt_pk_bf16_f32 v66, v35, v37
	v_lshlrev_b32_e32 v35, 16, v139
	v_and_b32_e32 v37, 0xffff0000, v139
	v_add_f32_e32 v35, v120, v35
	v_add_f32_e32 v37, v121, v37
	v_cvt_pk_bf16_f32 v67, v35, v37
	v_add_u32_e32 v35, s28, v77
	v_bfe_u32 v37, v54, 16, 1
	v_add3_u32 v37, v54, v37, s22
	v_add3_u32 v39, v35, v86, v87
	ds_write_b16_d16_hi v39, v37
	v_bfe_u32 v37, v55, 16, 1
	v_add3_u32 v37, v55, v37, s22
	ds_write_b16_d16_hi v39, v37 offset:272
	v_bfe_u32 v37, v50, 16, 1
	v_add3_u32 v37, v50, v37, s22
	ds_write_b16_d16_hi v39, v37 offset:544
	v_bfe_u32 v37, v51, 16, 1
	v_add3_u32 v37, v51, v37, s22
	ds_write_b16_d16_hi v39, v37 offset:816
	v_bfe_u32 v37, v56, 16, 1
	v_add3_u32 v37, v56, v37, s22
	v_add3_u32 v35, v35, v88, v87
	ds_write_b16_d16_hi v35, v37
	v_bfe_u32 v37, v57, 16, 1
	v_add3_u32 v37, v57, v37, s22
	ds_write_b16_d16_hi v35, v37 offset:272
	v_bfe_u32 v37, v52, 16, 1
	v_add3_u32 v37, v52, v37, s22
	ds_write_b16_d16_hi v35, v37 offset:544
	v_bfe_u32 v37, v53, 16, 1
	v_add_u32_e32 v118, s10, v103
	v_add3_u32 v37, v53, v37, s22
	v_ashrrev_i32_e32 v119, 31, v118
	ds_write_b16_d16_hi v35, v37 offset:816
	v_lshl_add_u32 v35, v26, 1, s27
	v_lshl_add_u64 v[118:119], v[118:119], 0, s[8:9]
	v_lshl_add_u32 v37, v200, 1, s27
	v_add_u32_e32 v39, v35, v68
	v_lshlrev_b64 v[118:119], 8, v[118:119]
	ds_write_b128 v39, v[4:7]
	v_add_u32_e32 v39, v37, v69
	v_add_u32_e32 v35, v35, v70
	v_lshl_add_u64 v[118:119], v[44:45], 0, v[118:119]
	ds_write_b128 v39, v[12:15] offset:18432
	ds_write_b128 v35, v[8:11]
	v_add_u32_e32 v35, v37, v71
	global_store_dwordx2 v[118:119], v[66:67], off
	ds_write_b128 v35, v[16:19] offset:18432
	s_and_saveexec_b64 s[10:11], vcc
	v_add3_u32 v35, s27, v72, v73
	ds_write_b128 v35, v[0:3] offset:35840
	s_or_b64 exec, exec, s[10:11]
	s_cmpk_gt_u32 s26, 0x81
	s_cbranch_scc1 .LBB0_549
	s_add_i32 s26, s17, 0x80
	s_and_b64 s[10:11], s[4:5], exec
	s_cselect_b32 s26, s26, s13
	s_add_i32 s10, s12, s16
	s_ashr_i32 s11, s10, 31
	s_lshl_b64 s[10:11], s[10:11], 14
	v_lshl_add_u64 v[4:5], v[46:47], 0, s[10:11]
	v_mov_b32_e32 v35, v21
	v_lshl_add_u64 v[6:7], v[4:5], 0, v[20:21]
	v_lshl_add_u64 v[8:9], v[4:5], 0, v[34:35]
	global_load_dwordx4 v[4:7], v[6:7], off
	s_nop 0
	global_load_dwordx4 v[8:11], v[8:9], off
	s_and_saveexec_b64 s[10:11], vcc
	s_cbranch_execz .LBB0_548
	v_add_u32_e32 v0, s26, v102
	v_ashrrev_i32_e32 v1, 31, v0
	v_lshl_add_u64 v[0:1], v[40:41], 0, v[0:1]
	v_lshlrev_b64 v[0:1], 9, v[0:1]
	v_lshl_add_u64 v[0:1], v[42:43], 0, v[0:1]
	global_load_dwordx4 v[0:3], v[0:1], off
; #define H2_WRITE(bf_) { bf16_t* B_ = L + (bf_) * 20480; \
;         _Pragma("unroll") for (int i2 = 0; i2 < 2; ++i2) { const int ch = tid + 512 * i2; *(u32x4*)(B_ + (ch >> 3) * 72 + (ch & 7) * 8) = kur[i2]; *(u32x4*)(B_ + 9216 + (ch >> 4) * 136 + (ch & 15) * 8) = qcr[i2]; } \
;         if (tid < 256) *(u32x4*)(B_ + 9216 + 8704 + vs * 40 + vc8) = vqr; }
; DI void hgrn_h2(const Params& p, int it, unsigned char* lds) {
;     ...
;         if (n + 1 < 132) { H2_WRITE(cur ^ 1);
; #pragma unroll
;             for (int j = 0; j < 2; ++j) decc[j] = decr[j];
;             oinc = oinr; }
.LBB0_548:
	s_or_b64 exec, exec, s[10:11]
	s_add_i32 s10, s15, s16
	s_ashr_i32 s11, s10, 31
	s_lshl_b64 s[10:11], s[10:11], 9
	v_lshl_add_u64 v[12:13], v[32:33], 0, s[10:11]
	s_add_i32 s10, s14, s16
	s_ashr_i32 s11, s10, 31
	v_add_u32_e32 v18, s26, v104
	s_lshl_b64 s[10:11], s[10:11], 14
	v_ashrrev_i32_e32 v19, 31, v18
	v_lshl_add_u64 v[16:17], v[30:31], 0, s[10:11]
	v_mov_b32_e32 v37, v21
	v_lshl_add_u64 v[18:19], v[18:19], 0, s[8:9]
	v_lshl_add_u64 v[14:15], v[16:17], 0, v[36:37]
	v_mov_b32_e32 v39, v21
	v_lshlrev_b64 v[18:19], 8, v[18:19]
	global_load_dword v37, v[12:13], off
	global_load_dword v35, v[12:13], off offset:64
	s_nop 0
	global_load_dwordx4 v[12:15], v[14:15], off
	v_lshl_add_u64 v[16:17], v[16:17], 0, v[38:39]
	v_lshl_add_u64 v[66:67], v[44:45], 0, v[18:19]
	global_load_dwordx4 v[16:19], v[16:17], off
	s_nop 0
	global_load_dwordx2 v[66:67], v[66:67], off
	s_branch .LBB0_550
.LBB0_549:
	v_mov_b32_e32 v35, v58
	v_mov_b32_e32 v37, v60
	v_mov_b64_e32 v[66:67], v[48:49]
.LBB0_550:
	s_add_i32 s16, s16, 1
	s_add_i32 s17, s17, 64
	s_sub_i32 s13, s13, 64
	s_cmpk_lg_i32 s16, 0x7f
	s_waitcnt lgkmcnt(0)
	s_barrier
	s_cbranch_scc0 .LBB0_515
	v_mov_b32_e32 v62, v58
	v_mov_b32_e32 v64, v60
	s_waitcnt vmcnt(4)
	v_mov_b32_e32 v60, v37
	s_waitcnt vmcnt(3)
	v_mov_b32_e32 v58, v35
	s_branch .LBB0_543

; #define PG8_STAGE(bufoff, gbase, voff) do { _Pragma("unroll") for (int _i = 0; _i < 2; ++_i) \
;         __builtin_amdgcn_global_load_lds((const unsigned*)((const char*)(gbase) + (voff)[_i]), (LAS unsigned*)(lds + (bufoff) + ldsw + _i * 8192), 16, 0, 0); } while (0)
; #define PG8_LDA(dst, b, h) do { _Pragma("unroll") for (int m = 0; m < 4; ++m) _Pragma("unroll") for (int k = 0; k < 2; ++k) dst[m][k] = *(const LAS bf16x8*)(lds + PG8_SA(b, h) + aoff + m * 2048 + k * 1024); } while (0)
; #define PG8_LDB(dst, b, h) do { _Pragma("unroll") for (int n = 0; n < 2; ++n) _Pragma("unroll") for (int k = 0; k < 2; ++k) dst[n][k] = *(const LAS bf16x8*)(lds + PG8_SB(b, h) + boff + n * 2048 + k * 1024); } while (0)
; #define PG8_MMA(ai, bj, At, Bt) do { __builtin_amdgcn_s_setprio(1); _Pragma("unroll") for (int m = 0; m < 4; ++m) _Pragma("unroll") for (int n = 0; n < 2; ++n) _Pragma("unroll") for (int k = 0; k < 2; ++k) \
;         acc[ai][bj][m][n] = __builtin_amdgcn_mfma_f32_16x16x32_bf16(Bt[n][k], At[m][k], acc[ai][bj][m][n], 0, 0, 0); __builtin_amdgcn_s_setprio(0); } while (0)
; #define PG8_WAIT_V(n) asm volatile("s_waitcnt vmcnt(" #n ")" ::: "memory")
; #define PG8_WAIT_L(n) asm volatile("s_waitcnt lgkmcnt(" #n ")" ::: "memory")
; #define PG8_BAR __builtin_amdgcn_s_barrier()
; #define PG8_SCHED __builtin_amdgcn_sched_barrier(0)
; template <class Epi, class Sched>
; DI void gemm_phase(LAS unsigned char* lds, const Gemm g, const Sched& S, const Epi& E) {
;     ...
;             PG8_LDB(B0, 0, 0); PG8_SCHED; PG8_LDA(At, 0, 0); PG8_STAGE(PG8_SA(1, 1), a1 + hstep, voffA);
;             PG8_WAIT_L(8); PG8_BAR; PG8_WAIT_L(0); PG8_MMA(0, 0, At, B0); PG8_BAR; PG8_SCHED;
;             PG8_LDB(B1, 0, 1); PG8_STAGE(PG8_SB(0, 0), b2, voffB);
;             PG8_BAR; PG8_WAIT_L(0); PG8_MMA(0, 1, At, B1); PG8_BAR;
;             PG8_LDA(At, 0, 1); PG8_STAGE(PG8_SA(0, 0), a2, voffA);
;             PG8_BAR; PG8_WAIT_L(0); PG8_MMA(1, 0, At, B0); PG8_BAR; PG8_SCHED;
;             PG8_STAGE(PG8_SB(0, 1), b2 + hstep, voffB);
;             PG8_WAIT_V(6); PG8_BAR; PG8_MMA(1, 1, At, B1); PG8_BAR;
.LBB0_911:
	ds_read_b128 v[128:131], v161
	ds_read_b128 v[132:135], v161 offset:1024
	ds_read_b128 v[136:139], v161 offset:2048
	ds_read_b128 v[140:143], v161 offset:3072
	s_add_u32 s28, s26, 0xfff00080
	s_addc_u32 s29, s27, -1
	s_cmp_eq_u32 s88, 60
	s_cselect_b32 s31, s25, s29
	s_cselect_b32 s30, s83, s28
	s_cselect_b32 s29, s84, s87
	s_cselect_b32 s28, s85, s86
	v_lshl_add_u64 v[158:159], s[26:27], 0, v[150:151]
	s_add_i32 m0, s5, 0xc000
	ds_read_b128 v[154:157], v162
	ds_read_b128 v[166:169], v162 offset:1024
	ds_read_b128 v[170:173], v162 offset:2048
	ds_read_b128 v[174:177], v162 offset:3072
	ds_read_b128 v[178:181], v162 offset:4096
	ds_read_b128 v[182:185], v162 offset:5120
	ds_read_b128 v[186:189], v162 offset:6144
	ds_read_b128 v[190:193], v162 offset:7168
	global_load_lds_dwordx4 v[158:159], off
	v_lshl_add_u64 v[158:159], s[26:27], 0, v[152:153]
	s_add_i32 m0, s5, 0xe000
	s_nop 0
	global_load_lds_dwordx4 v[158:159], off
	s_waitcnt lgkmcnt(8)
	s_barrier
	s_waitcnt lgkmcnt(0)
	s_setprio 1
	s_waitcnt lgkmcnt(0)
	v_mfma_f32_16x16x32_bf16 v[124:127], v[128:131], v[154:157], v[124:127]
	v_mfma_f32_16x16x32_bf16 v[120:123], v[136:139], v[154:157], v[120:123]
	v_mfma_f32_16x16x32_bf16 v[108:111], v[128:131], v[170:173], v[108:111]
	v_mfma_f32_16x16x32_bf16 v[104:107], v[136:139], v[170:173], v[104:107]
	v_mfma_f32_16x16x32_bf16 v[92:95], v[128:131], v[178:181], v[92:95]
	v_mfma_f32_16x16x32_bf16 v[88:91], v[136:139], v[178:181], v[88:91]
	v_mfma_f32_16x16x32_bf16 v[76:79], v[128:131], v[186:189], v[76:79]
	v_mfma_f32_16x16x32_bf16 v[72:75], v[136:139], v[186:189], v[72:75]
	v_mfma_f32_16x16x32_bf16 v[124:127], v[132:135], v[166:169], v[124:127]
	v_mfma_f32_16x16x32_bf16 v[120:123], v[140:143], v[166:169], v[120:123]
	v_mfma_f32_16x16x32_bf16 v[108:111], v[132:135], v[174:177], v[108:111]
	v_mfma_f32_16x16x32_bf16 v[104:107], v[140:143], v[174:177], v[104:107]
	v_mfma_f32_16x16x32_bf16 v[92:95], v[132:135], v[182:185], v[92:95]
	v_mfma_f32_16x16x32_bf16 v[88:91], v[140:143], v[182:185], v[88:91]
	v_mfma_f32_16x16x32_bf16 v[76:79], v[132:135], v[190:193], v[76:79]
	v_mfma_f32_16x16x32_bf16 v[72:75], v[140:143], v[190:193], v[72:75]
	s_setprio 0
	s_barrier
	s_add_i32 s89, s59, s23
	v_lshl_add_u64 v[158:159], s[28:29], 0, v[144:145]
	s_mov_b32 m0, s89
	ds_read_b128 v[198:201], v163
	ds_read_b128 v[202:205], v163 offset:1024
	ds_read_b128 v[206:209], v163 offset:2048
	ds_read_b128 v[210:213], v163 offset:3072
	global_load_lds_dwordx4 v[158:159], off
	v_lshl_add_u64 v[194:195], s[28:29], 0, v[146:147]
	s_add_i32 m0, s89, 0x2000
	s_nop 0
	global_load_lds_dwordx4 v[194:195], off
	s_barrier
	s_waitcnt lgkmcnt(0)
	s_setprio 1
	s_waitcnt lgkmcnt(0)
	v_mfma_f32_16x16x32_bf16 v[116:119], v[198:201], v[154:157], v[116:119]
	v_mfma_f32_16x16x32_bf16 v[112:115], v[206:209], v[154:157], v[112:115]
	v_mfma_f32_16x16x32_bf16 v[100:103], v[198:201], v[170:173], v[100:103]
	v_mfma_f32_16x16x32_bf16 v[96:99], v[206:209], v[170:173], v[96:99]
	v_mfma_f32_16x16x32_bf16 v[84:87], v[198:201], v[178:181], v[84:87]
	v_mfma_f32_16x16x32_bf16 v[80:83], v[206:209], v[178:181], v[80:83]
	v_mfma_f32_16x16x32_bf16 v[68:71], v[198:201], v[186:189], v[68:71]
	v_mfma_f32_16x16x32_bf16 v[64:67], v[206:209], v[186:189], v[64:67]
	v_mfma_f32_16x16x32_bf16 v[116:119], v[202:205], v[166:169], v[116:119]
	v_mfma_f32_16x16x32_bf16 v[112:115], v[210:213], v[166:169], v[112:115]
	v_mfma_f32_16x16x32_bf16 v[100:103], v[202:205], v[174:177], v[100:103]
	v_mfma_f32_16x16x32_bf16 v[96:99], v[210:213], v[174:177], v[96:99]
	v_mfma_f32_16x16x32_bf16 v[84:87], v[202:205], v[182:185], v[84:87]
	v_mfma_f32_16x16x32_bf16 v[80:83], v[210:213], v[182:185], v[80:83]
	v_mfma_f32_16x16x32_bf16 v[68:71], v[202:205], v[190:193], v[68:71]
	v_mfma_f32_16x16x32_bf16 v[64:67], v[210:213], v[190:193], v[64:67]
	s_setprio 0
	s_mov_b32 m0, s5
	v_lshl_add_u64 v[214:215], s[30:31], 0, v[144:145]
	s_barrier
	ds_read_b128 v[154:157], v162 offset:16384
	ds_read_b128 v[166:169], v162 offset:17408
	ds_read_b128 v[170:173], v162 offset:18432
	ds_read_b128 v[174:177], v162 offset:19456
	ds_read_b128 v[178:181], v162 offset:20480
	ds_read_b128 v[182:185], v162 offset:21504
	ds_read_b128 v[186:189], v162 offset:22528
	ds_read_b128 v[190:193], v162 offset:23552
	global_load_lds_dwordx4 v[214:215], off
	v_lshl_add_u64 v[216:217], s[30:31], 0, v[146:147]
	s_mov_b32 m0, s35
	s_nop 0
	global_load_lds_dwordx4 v[216:217], off
	s_barrier
	s_waitcnt lgkmcnt(0)
	s_setprio 1
	s_waitcnt lgkmcnt(0)
	v_mfma_f32_16x16x32_bf16 v[60:63], v[128:131], v[154:157], v[60:63]
	v_mfma_f32_16x16x32_bf16 v[56:59], v[136:139], v[154:157], v[56:59]
	v_mfma_f32_16x16x32_bf16 v[44:47], v[128:131], v[170:173], v[44:47]
	v_mfma_f32_16x16x32_bf16 v[40:43], v[136:139], v[170:173], v[40:43]
	v_mfma_f32_16x16x32_bf16 v[28:31], v[128:131], v[178:181], v[28:31]
	v_mfma_f32_16x16x32_bf16 v[20:23], v[136:139], v[178:181], v[20:23]
	v_mfma_f32_16x16x32_bf16 v[24:27], v[128:131], v[186:189], v[24:27]
	v_mfma_f32_16x16x32_bf16 v[16:19], v[136:139], v[186:189], v[16:19]
	v_mfma_f32_16x16x32_bf16 v[60:63], v[132:135], v[166:169], v[60:63]
	v_mfma_f32_16x16x32_bf16 v[56:59], v[140:143], v[166:169], v[56:59]
	v_mfma_f32_16x16x32_bf16 v[44:47], v[132:135], v[174:177], v[44:47]
	v_mfma_f32_16x16x32_bf16 v[40:43], v[140:143], v[174:177], v[40:43]
	v_mfma_f32_16x16x32_bf16 v[28:31], v[132:135], v[182:185], v[28:31]
	v_mfma_f32_16x16x32_bf16 v[20:23], v[140:143], v[182:185], v[20:23]
	v_mfma_f32_16x16x32_bf16 v[24:27], v[132:135], v[190:193], v[24:27]
	v_mfma_f32_16x16x32_bf16 v[16:19], v[140:143], v[190:193], v[16:19]
	s_setprio 0
	s_barrier
; #define PG8_STAGE(bufoff, gbase, voff) do { _Pragma("unroll") for (int _i = 0; _i < 2; ++_i) \
;         __builtin_amdgcn_global_load_lds((const unsigned*)((const char*)(gbase) + (voff)[_i]), (LAS unsigned*)(lds + (bufoff) + ldsw + _i * 8192), 16, 0, 0); } while (0)
; #define PG8_LDA(dst, b, h) do { _Pragma("unroll") for (int m = 0; m < 4; ++m) _Pragma("unroll") for (int k = 0; k < 2; ++k) dst[m][k] = *(const LAS bf16x8*)(lds + PG8_SA(b, h) + aoff + m * 2048 + k * 1024); } while (0)
; #define PG8_LDB(dst, b, h) do { _Pragma("unroll") for (int n = 0; n < 2; ++n) _Pragma("unroll") for (int k = 0; k < 2; ++k) dst[n][k] = *(const LAS bf16x8*)(lds + PG8_SB(b, h) + boff + n * 2048 + k * 1024); } while (0)
; #define PG8_MMA(ai, bj, At, Bt) do { __builtin_amdgcn_s_setprio(1); _Pragma("unroll") for (int m = 0; m < 4; ++m) _Pragma("unroll") for (int n = 0; n < 2; ++n) _Pragma("unroll") for (int k = 0; k < 2; ++k) \
;         acc[ai][bj][m][n] = __builtin_amdgcn_mfma_f32_16x16x32_bf16(Bt[n][k], At[m][k], acc[ai][bj][m][n], 0, 0, 0); __builtin_amdgcn_s_setprio(0); } while (0)
; #define PG8_WAIT_V(n) asm volatile("s_waitcnt vmcnt(" #n ")" ::: "memory")
; #define PG8_WAIT_L(n) asm volatile("s_waitcnt lgkmcnt(" #n ")" ::: "memory")
; #define PG8_BAR __builtin_amdgcn_s_barrier()
; #define PG8_SCHED __builtin_amdgcn_sched_barrier(0)
; template <class Epi, class Sched>
; DI void gemm_phase(LAS unsigned char* lds, const Gemm g, const Sched& S, const Epi& E) {
;     ...
;             PG8_WAIT_V(6); PG8_BAR; PG8_MMA(1, 1, At, B1); PG8_BAR;
;             PG8_LDB(B0, 1, 0); PG8_SCHED; PG8_LDA(At, 1, 0); PG8_STAGE(PG8_SA(0, 1), a2 + hstep, voffA);
;             PG8_WAIT_L(8); PG8_BAR; PG8_WAIT_L(0); PG8_MMA(0, 0, At, B0); PG8_BAR; PG8_SCHED;
;             PG8_LDB(B1, 1, 1); PG8_STAGE(PG8_SB(1, 0), b3, voffB);
;             PG8_BAR; PG8_WAIT_L(0); PG8_MMA(0, 1, At, B1); PG8_BAR;
;             PG8_LDA(At, 1, 1); PG8_STAGE(PG8_SA(1, 0), a3, voffA);
;             PG8_BAR; PG8_WAIT_L(0); PG8_MMA(1, 0, At, B0); PG8_BAR; PG8_SCHED;
	s_add_u32 s90, s28, 0x100000
	s_addc_u32 s91, s29, 0
	s_add_i32 s89, s60, s23
	v_lshl_add_u64 v[128:129], s[90:91], 0, v[144:145]
	s_mov_b32 m0, s89
	s_nop 0
	global_load_lds_dwordx4 v[128:129], off
	v_lshl_add_u64 v[128:129], s[90:91], 0, v[146:147]
	s_add_i32 m0, s89, 0x2000
	s_nop 0
	global_load_lds_dwordx4 v[128:129], off
	s_waitcnt vmcnt(6)
	s_barrier
	s_setprio 1
	v_mfma_f32_16x16x32_bf16 v[52:55], v[198:201], v[154:157], v[52:55]
	v_mfma_f32_16x16x32_bf16 v[48:51], v[206:209], v[154:157], v[48:51]
	v_mfma_f32_16x16x32_bf16 v[36:39], v[198:201], v[170:173], v[36:39]
	v_mfma_f32_16x16x32_bf16 v[32:35], v[206:209], v[170:173], v[32:35]
	v_mfma_f32_16x16x32_bf16 v[12:15], v[198:201], v[178:181], v[12:15]
	v_mfma_f32_16x16x32_bf16 v[4:7], v[206:209], v[178:181], v[4:7]
	v_mfma_f32_16x16x32_bf16 v[8:11], v[198:201], v[186:189], v[8:11]
	v_mfma_f32_16x16x32_bf16 v[0:3], v[206:209], v[186:189], v[0:3]
	v_mfma_f32_16x16x32_bf16 v[52:55], v[202:205], v[166:169], v[52:55]
	v_mfma_f32_16x16x32_bf16 v[48:51], v[210:213], v[166:169], v[48:51]
	v_mfma_f32_16x16x32_bf16 v[36:39], v[202:205], v[174:177], v[36:39]
	v_mfma_f32_16x16x32_bf16 v[32:35], v[210:213], v[174:177], v[32:35]
	v_mfma_f32_16x16x32_bf16 v[12:15], v[202:205], v[182:185], v[12:15]
	v_mfma_f32_16x16x32_bf16 v[4:7], v[210:213], v[182:185], v[4:7]
	v_mfma_f32_16x16x32_bf16 v[8:11], v[202:205], v[190:193], v[8:11]
	v_mfma_f32_16x16x32_bf16 v[0:3], v[210:213], v[190:193], v[0:3]
	s_setprio 0
	s_add_i32 s89, 0, 0x18000
	v_add_u32_e32 v140, s89, v160
	s_barrier
	ds_read_b128 v[128:131], v140
	ds_read_b128 v[132:135], v140 offset:1024
	ds_read_b128 v[136:139], v140 offset:2048
	ds_read_b128 v[140:143], v140 offset:3072
	s_add_u32 s30, s30, 0x100000
	s_addc_u32 s31, s31, 0
	s_mov_b32 m0, s36
	v_lshl_add_u64 v[198:199], s[30:31], 0, v[144:145]
	ds_read_b128 v[154:157], v162 offset:32768
	ds_read_b128 v[166:169], v162 offset:33792
	ds_read_b128 v[170:173], v162 offset:34816
	ds_read_b128 v[174:177], v162 offset:35840
	ds_read_b128 v[178:181], v162 offset:36864
	ds_read_b128 v[182:185], v162 offset:37888
	ds_read_b128 v[186:189], v162 offset:38912
	ds_read_b128 v[190:193], v162 offset:39936
	global_load_lds_dwordx4 v[198:199], off
	v_lshl_add_u64 v[198:199], s[30:31], 0, v[146:147]
	s_mov_b32 m0, s37
	s_nop 0
	global_load_lds_dwordx4 v[198:199], off
	s_waitcnt lgkmcnt(8)
	s_barrier
	s_waitcnt lgkmcnt(0)
	s_setprio 1
	s_waitcnt lgkmcnt(0)
	v_mfma_f32_16x16x32_bf16 v[124:127], v[128:131], v[154:157], v[124:127]
	v_mfma_f32_16x16x32_bf16 v[120:123], v[136:139], v[154:157], v[120:123]
	v_mfma_f32_16x16x32_bf16 v[108:111], v[128:131], v[170:173], v[108:111]
	v_mfma_f32_16x16x32_bf16 v[104:107], v[136:139], v[170:173], v[104:107]
	v_mfma_f32_16x16x32_bf16 v[92:95], v[128:131], v[178:181], v[92:95]
	v_mfma_f32_16x16x32_bf16 v[88:91], v[136:139], v[178:181], v[88:91]
	v_mfma_f32_16x16x32_bf16 v[76:79], v[128:131], v[186:189], v[76:79]
	v_mfma_f32_16x16x32_bf16 v[72:75], v[136:139], v[186:189], v[72:75]
	v_mfma_f32_16x16x32_bf16 v[124:127], v[132:135], v[166:169], v[124:127]
	v_mfma_f32_16x16x32_bf16 v[120:123], v[140:143], v[166:169], v[120:123]
	v_mfma_f32_16x16x32_bf16 v[108:111], v[132:135], v[174:177], v[108:111]
	v_mfma_f32_16x16x32_bf16 v[104:107], v[140:143], v[174:177], v[104:107]
	v_mfma_f32_16x16x32_bf16 v[92:95], v[132:135], v[182:185], v[92:95]
	v_mfma_f32_16x16x32_bf16 v[88:91], v[140:143], v[182:185], v[88:91]
	v_mfma_f32_16x16x32_bf16 v[76:79], v[132:135], v[190:193], v[76:79]
	v_mfma_f32_16x16x32_bf16 v[72:75], v[140:143], v[190:193], v[72:75]
	s_setprio 0
	s_barrier
	s_add_i32 s30, 0, 0x1c000
	s_add_i32 s31, s89, s23
	v_add_u32_e32 v148, s30, v160
	v_lshl_add_u64 v[158:159], v[158:159], 0, s[16:17]
	s_mov_b32 m0, s31
	ds_read_b128 v[198:201], v148
	ds_read_b128 v[202:205], v148 offset:1024
	ds_read_b128 v[206:209], v148 offset:2048
	ds_read_b128 v[210:213], v148 offset:3072
	global_load_lds_dwordx4 v[158:159], off
	v_lshl_add_u64 v[158:159], v[194:195], 0, s[16:17]
	s_add_i32 m0, s31, 0x2000
	s_nop 0
	global_load_lds_dwordx4 v[158:159], off
	s_barrier
	s_waitcnt lgkmcnt(0)
	s_setprio 1
	s_waitcnt lgkmcnt(0)
	v_mfma_f32_16x16x32_bf16 v[116:119], v[198:201], v[154:157], v[116:119]
	v_mfma_f32_16x16x32_bf16 v[112:115], v[206:209], v[154:157], v[112:115]
	v_mfma_f32_16x16x32_bf16 v[100:103], v[198:201], v[170:173], v[100:103]
	v_mfma_f32_16x16x32_bf16 v[96:99], v[206:209], v[170:173], v[96:99]
	v_mfma_f32_16x16x32_bf16 v[84:87], v[198:201], v[178:181], v[84:87]
	v_mfma_f32_16x16x32_bf16 v[80:83], v[206:209], v[178:181], v[80:83]
	v_mfma_f32_16x16x32_bf16 v[68:71], v[198:201], v[186:189], v[68:71]
	v_mfma_f32_16x16x32_bf16 v[64:67], v[206:209], v[186:189], v[64:67]
	v_mfma_f32_16x16x32_bf16 v[116:119], v[202:205], v[166:169], v[116:119]
	v_mfma_f32_16x16x32_bf16 v[112:115], v[210:213], v[166:169], v[112:115]
	v_mfma_f32_16x16x32_bf16 v[100:103], v[202:205], v[174:177], v[100:103]
	v_mfma_f32_16x16x32_bf16 v[96:99], v[210:213], v[174:177], v[96:99]
	v_mfma_f32_16x16x32_bf16 v[84:87], v[202:205], v[182:185], v[84:87]
	v_mfma_f32_16x16x32_bf16 v[80:83], v[210:213], v[182:185], v[80:83]
	v_mfma_f32_16x16x32_bf16 v[68:71], v[202:205], v[190:193], v[68:71]
	v_mfma_f32_16x16x32_bf16 v[64:67], v[210:213], v[190:193], v[64:67]
	s_setprio 0
	s_mov_b32 m0, s50
	v_lshl_add_u64 v[158:159], v[214:215], 0, s[16:17]
	s_barrier
	ds_read_b128 v[154:157], v162 offset:49152
	ds_read_b128 v[166:169], v162 offset:50176
	ds_read_b128 v[170:173], v162 offset:51200
	ds_read_b128 v[174:177], v162 offset:52224
	ds_read_b128 v[178:181], v162 offset:53248
	ds_read_b128 v[182:185], v162 offset:54272
	ds_read_b128 v[186:189], v162 offset:55296
	ds_read_b128 v[190:193], v162 offset:56320
	global_load_lds_dwordx4 v[158:159], off
	v_lshl_add_u64 v[158:159], v[216:217], 0, s[16:17]
	s_mov_b32 m0, s51
	s_nop 0
	global_load_lds_dwordx4 v[158:159], off
	s_barrier
; #define PG8_STAGE(bufoff, gbase, voff) do { _Pragma("unroll") for (int _i = 0; _i < 2; ++_i) \
;         __builtin_amdgcn_global_load_lds((const unsigned*)((const char*)(gbase) + (voff)[_i]), (LAS unsigned*)(lds + (bufoff) + ldsw + _i * 8192), 16, 0, 0); } while (0)
; #define PG8_MMA(ai, bj, At, Bt) do { __builtin_amdgcn_s_setprio(1); _Pragma("unroll") for (int m = 0; m < 4; ++m) _Pragma("unroll") for (int n = 0; n < 2; ++n) _Pragma("unroll") for (int k = 0; k < 2; ++k) \
;         acc[ai][bj][m][n] = __builtin_amdgcn_mfma_f32_16x16x32_bf16(Bt[n][k], At[m][k], acc[ai][bj][m][n], 0, 0, 0); __builtin_amdgcn_s_setprio(0); } while (0)
; template <class Epi, class Sched>
; DI void gemm_phase(LAS unsigned char* lds, const Gemm g, const Sched& S, const Epi& E) {
;     ...
;             PG8_STAGE(PG8_SB(1, 1), b3 + hstep, voffB);
;             PG8_WAIT_V(6); PG8_BAR; PG8_MMA(1, 1, At, B1); PG8_BAR;
;     DI bool operator()(f32x4 (&acc)[2][2][4][2], const pg8::Unit& u, int wr, int wc, int fr, int fq) const {
;     ...
;         const int pm = __builtin_amdgcn_readfirstlane(u.pm), pn = __builtin_amdgcn_readfirstlane(u.pn);
;         const unsigned loff = (unsigned)(((wr * 64 + fr) * DM + wc * 32 + 4 * fq) * 4);
;         const unsigned coff = (unsigned)((wc * 32 + 4 * fq) * 4);
;         const char* xt = (const char*)(x + (size_t)pm * 256 * DM + pn * 256);
;         char* ot = (char*)(out + (size_t)pm * 256 * DM + pn * 256);
;         const char* gt = (const char*)(mod + (size_t)(pm >> 5) * 12288 + 8192 + pn * 256);
;         {
;             f32x4 gv[2][2];
; #pragma unroll
;             for (int bj = 0; bj < 2; ++bj)
; #pragma unroll
;                 for (int n = 0; n < 2; ++n) gv[bj][n] = *(const f32x4*)(gt + coff + (bj * 128 + n * 16) * 4);
; #pragma unroll
;             for (int ai = 0; ai < 2; ++ai)
; #pragma unroll
;                 for (int m = 0; m < 4; ++m) { const char* xr = xt + (size_t)(ai * 128 + m * 16) * DM * 4;
; #pragma unroll
;                     for (int bj = 0; bj < 2; ++bj)
; #pragma unroll
;                         for (int n = 0; n < 2; ++n) { const f32x4 xv = *(const f32x4*)(xr + loff + (bj * 128 + n * 16) * 4); acc[ai][bj][m][n] = xv * ALPHA_F + gv[bj][n] * acc[ai][bj][m][n]; }
;                     asm volatile("" : "+v"(acc[ai][0][m][0]), "+v"(acc[ai][0][m][1]), "+v"(acc[ai][1][m][0]), "+v"(acc[ai][1][m][1]) :: "memory"); }
	s_waitcnt lgkmcnt(0)
	s_setprio 1
	s_waitcnt lgkmcnt(0)
	v_mfma_f32_16x16x32_bf16 v[60:63], v[128:131], v[154:157], v[60:63]
	v_mfma_f32_16x16x32_bf16 v[56:59], v[136:139], v[154:157], v[56:59]
	v_mfma_f32_16x16x32_bf16 v[44:47], v[128:131], v[170:173], v[44:47]
	v_mfma_f32_16x16x32_bf16 v[40:43], v[136:139], v[170:173], v[40:43]
	v_mfma_f32_16x16x32_bf16 v[28:31], v[128:131], v[178:181], v[28:31]
	v_mfma_f32_16x16x32_bf16 v[20:23], v[136:139], v[178:181], v[20:23]
	v_mfma_f32_16x16x32_bf16 v[24:27], v[128:131], v[186:189], v[24:27]
	v_mfma_f32_16x16x32_bf16 v[16:19], v[136:139], v[186:189], v[16:19]
	v_mfma_f32_16x16x32_bf16 v[60:63], v[132:135], v[166:169], v[60:63]
	v_mfma_f32_16x16x32_bf16 v[56:59], v[140:143], v[166:169], v[56:59]
	v_mfma_f32_16x16x32_bf16 v[44:47], v[132:135], v[174:177], v[44:47]
	v_mfma_f32_16x16x32_bf16 v[40:43], v[140:143], v[174:177], v[40:43]
	v_mfma_f32_16x16x32_bf16 v[28:31], v[132:135], v[182:185], v[28:31]
	v_mfma_f32_16x16x32_bf16 v[20:23], v[140:143], v[182:185], v[20:23]
	v_mfma_f32_16x16x32_bf16 v[24:27], v[132:135], v[190:193], v[24:27]
	v_mfma_f32_16x16x32_bf16 v[16:19], v[140:143], v[190:193], v[16:19]
	s_setprio 0
	s_barrier
	s_add_u32 s28, s28, 0x100080
	s_addc_u32 s29, s29, 0
	s_add_i32 s30, s30, s23
	v_lshl_add_u64 v[128:129], s[28:29], 0, v[144:145]
	s_mov_b32 m0, s30
	s_nop 0
	global_load_lds_dwordx4 v[128:129], off
	v_lshl_add_u64 v[128:129], s[28:29], 0, v[146:147]
	s_add_i32 m0, s30, 0x2000
	s_nop 0
	global_load_lds_dwordx4 v[128:129], off
	s_waitcnt vmcnt(6)
	s_barrier
	s_setprio 1
	v_mfma_f32_16x16x32_bf16 v[52:55], v[198:201], v[154:157], v[52:55]
	v_mfma_f32_16x16x32_bf16 v[48:51], v[206:209], v[154:157], v[48:51]
	v_mfma_f32_16x16x32_bf16 v[36:39], v[198:201], v[170:173], v[36:39]
	v_mfma_f32_16x16x32_bf16 v[32:35], v[206:209], v[170:173], v[32:35]
	v_mfma_f32_16x16x32_bf16 v[12:15], v[198:201], v[178:181], v[12:15]
	v_mfma_f32_16x16x32_bf16 v[4:7], v[206:209], v[178:181], v[4:7]
	v_mfma_f32_16x16x32_bf16 v[8:11], v[198:201], v[186:189], v[8:11]
	v_mfma_f32_16x16x32_bf16 v[0:3], v[206:209], v[186:189], v[0:3]
	v_mfma_f32_16x16x32_bf16 v[52:55], v[202:205], v[166:169], v[52:55]
	v_mfma_f32_16x16x32_bf16 v[48:51], v[210:213], v[166:169], v[48:51]
	v_mfma_f32_16x16x32_bf16 v[36:39], v[202:205], v[174:177], v[36:39]
	v_mfma_f32_16x16x32_bf16 v[32:35], v[210:213], v[174:177], v[32:35]
	v_mfma_f32_16x16x32_bf16 v[12:15], v[202:205], v[182:185], v[12:15]
	v_mfma_f32_16x16x32_bf16 v[4:7], v[210:213], v[182:185], v[4:7]
	v_mfma_f32_16x16x32_bf16 v[8:11], v[202:205], v[190:193], v[8:11]
	v_mfma_f32_16x16x32_bf16 v[0:3], v[210:213], v[190:193], v[0:3]
	s_setprio 0
	s_add_i32 s88, s88, 2
	s_add_u32 s26, s26, 0x100
	s_addc_u32 s27, s27, 0
	s_add_u32 s86, s86, 0x100
	s_addc_u32 s87, s87, 0
	s_cmp_gt_u32 s88, 61
	s_barrier
	s_cbranch_scc0 .LBB0_911
	s_lshl_b32 s26, s4, 8
	s_ashr_i32 s28, s24, 5
	s_ashr_i32 s25, s24, 31
	s_ashr_i32 s27, s26, 31
	s_mul_hi_i32 s29, s28, 0xc000
	s_mul_i32 s28, s28, 0xc000
	v_mov_b32_e32 v171, v196
	s_add_u32 s28, s80, s28
	s_addc_u32 s29, s81, s29
	v_bfe_u32 v168, v171, 4, 2
	s_lshl_b64 s[26:27], s[26:27], 2
	v_bfe_u32 v173, v171, 6, 2
	v_lshlrev_b32_e32 v128, 4, v168
	s_add_u32 s28, s28, s26
	v_lshl_or_b32 v148, v173, 7, v128
	s_addc_u32 s29, s29, s27
	v_lshl_add_u64 v[128:129], s[28:29], 0, v[148:149]
	s_lshl_b64 s[28:29], s[24:25], 22
	v_ashrrev_i32_e32 v170, 8, v171
	s_add_u32 s28, s56, s28
	v_lshlrev_b32_e32 v172, 6, v170
	s_addc_u32 s29, s57, s29
	v_and_or_b32 v169, v171, 15, v172
	s_add_u32 s28, s28, s26
	v_lshl_or_b32 v154, v169, 14, v148
	s_addc_u32 s29, s29, s27
	v_add_co_u32_e32 v130, vcc, s58, v128
	global_load_dwordx4 v[174:177], v154, s[28:29]
	global_load_dwordx4 v[178:181], v154, s[28:29] offset:64
	global_load_dwordx4 v[182:185], v154, s[28:29] offset:512
	global_load_dwordx4 v[186:189], v154, s[28:29] offset:576
	v_addc_co_u32_e32 v131, vcc, 0, v129, vcc
	v_lshl_add_u64 v[128:129], v[128:129], 0, s[18:19]
	global_load_dwordx4 v[136:139], v[130:131], off
	global_load_dwordx4 v[140:143], v[128:129], off offset:64
	global_load_dwordx4 v[132:135], v[128:129], off offset:512
	s_nop 0
	global_load_dwordx4 v[128:131], v[128:129], off offset:576
	v_mov_b32_e32 v155, v149
	v_lshl_add_u64 v[156:157], s[28:29], 0, v[154:155]
	v_add_co_u32_e32 v158, vcc, 0x40000, v156
	s_nop 1
	v_addc_co_u32_e32 v159, vcc, 0, v157, vcc
	global_load_dwordx4 v[218:221], v[158:159], off
	global_load_dwordx4 v[222:225], v[158:159], off offset:64
	global_load_dwordx4 v[226:229], v[158:159], off offset:512
	global_load_dwordx4 v[230:233], v[158:159], off offset:576
	v_add_co_u32_e32 v158, vcc, 0x80000, v156
	s_nop 1
	v_addc_co_u32_e32 v159, vcc, 0, v157, vcc
	global_load_dwordx4 v[234:237], v[158:159], off
	global_load_dwordx4 v[238:241], v[158:159], off offset:64
	global_load_dwordx4 v[242:245], v[158:159], off offset:512
	global_load_dwordx4 v[246:249], v[158:159], off offset:576
	s_waitcnt vmcnt(8)
	v_pk_mul_f32 v[174:175], v[174:175], s[20:21] op_sel_hi:[1,0]
	v_pk_mul_f32 v[176:177], v[176:177], s[20:21] op_sel_hi:[1,0]
	v_pk_mul_f32 v[178:179], v[178:179], s[20:21] op_sel_hi:[1,0]
	v_pk_mul_f32 v[180:181], v[180:181], s[20:21] op_sel_hi:[1,0]
	v_pk_mul_f32 v[182:183], v[182:183], s[20:21] op_sel_hi:[1,0]
	v_pk_mul_f32 v[184:185], v[184:185], s[20:21] op_sel_hi:[1,0]
	v_pk_mul_f32 v[186:187], v[186:187], s[20:21] op_sel_hi:[1,0]
	v_pk_mul_f32 v[188:189], v[188:189], s[20:21] op_sel_hi:[1,0]
	v_pk_fma_f32 v[124:125], v[124:125], v[136:137], v[174:175]
	v_pk_fma_f32 v[126:127], v[126:127], v[138:139], v[176:177]
	v_pk_fma_f32 v[120:121], v[120:121], v[140:141], v[178:179]
	v_pk_fma_f32 v[122:123], v[122:123], v[142:143], v[180:181]
	v_pk_fma_f32 v[116:117], v[116:117], v[132:133], v[182:183]
	v_pk_fma_f32 v[118:119], v[118:119], v[134:135], v[184:185]
	v_pk_fma_f32 v[112:113], v[112:113], v[128:129], v[186:187]
	v_pk_fma_f32 v[114:115], v[114:115], v[130:131], v[188:189]
	v_add_co_u32_e32 v158, vcc, 0xc0000, v156
	s_nop 1
	v_addc_co_u32_e32 v159, vcc, 0, v157, vcc
	global_load_dwordx4 v[174:177], v[158:159], off
	global_load_dwordx4 v[178:181], v[158:159], off offset:64
	global_load_dwordx4 v[182:185], v[158:159], off offset:512
	global_load_dwordx4 v[186:189], v[158:159], off offset:576
	s_waitcnt vmcnt(8)
;     DI bool operator()(f32x4 (&acc)[2][2][4][2], const pg8::Unit& u, int wr, int wc, int fr, int fq) const {
;     ...
;             for (int ai = 0; ai < 2; ++ai)
; #pragma unroll
;                 for (int m = 0; m < 4; ++m) { const char* xr = xt + (size_t)(ai * 128 + m * 16) * DM * 4;
; #pragma unroll
;                     for (int bj = 0; bj < 2; ++bj)
; #pragma unroll
;                         for (int n = 0; n < 2; ++n) { const f32x4 xv = *(const f32x4*)(xr + loff + (bj * 128 + n * 16) * 4); acc[ai][bj][m][n] = xv * ALPHA_F + gv[bj][n] * acc[ai][bj][m][n]; }
;                     asm volatile("" : "+v"(acc[ai][0][m][0]), "+v"(acc[ai][0][m][1]), "+v"(acc[ai][1][m][0]), "+v"(acc[ai][1][m][1]) :: "memory"); }
	v_pk_mul_f32 v[218:219], v[218:219], s[20:21] op_sel_hi:[1,0]
	v_pk_mul_f32 v[220:221], v[220:221], s[20:21] op_sel_hi:[1,0]
	v_pk_mul_f32 v[222:223], v[222:223], s[20:21] op_sel_hi:[1,0]
	v_pk_mul_f32 v[224:225], v[224:225], s[20:21] op_sel_hi:[1,0]
	v_pk_mul_f32 v[226:227], v[226:227], s[20:21] op_sel_hi:[1,0]
	v_pk_mul_f32 v[228:229], v[228:229], s[20:21] op_sel_hi:[1,0]
	v_pk_mul_f32 v[230:231], v[230:231], s[20:21] op_sel_hi:[1,0]
	v_pk_mul_f32 v[232:233], v[232:233], s[20:21] op_sel_hi:[1,0]
	v_pk_fma_f32 v[108:109], v[108:109], v[136:137], v[218:219]
	v_pk_fma_f32 v[110:111], v[110:111], v[138:139], v[220:221]
	v_pk_fma_f32 v[104:105], v[104:105], v[140:141], v[222:223]
	v_pk_fma_f32 v[106:107], v[106:107], v[142:143], v[224:225]
	v_pk_fma_f32 v[100:101], v[100:101], v[132:133], v[226:227]
	v_pk_fma_f32 v[102:103], v[102:103], v[134:135], v[228:229]
	v_pk_fma_f32 v[96:97], v[96:97], v[128:129], v[230:231]
	v_pk_fma_f32 v[98:99], v[98:99], v[130:131], v[232:233]
	v_add_co_u32_e32 v158, vcc, 0x200000, v156
	s_nop 1
	v_addc_co_u32_e32 v159, vcc, 0, v157, vcc
	global_load_dwordx4 v[218:221], v[158:159], off
	global_load_dwordx4 v[222:225], v[158:159], off offset:64
	global_load_dwordx4 v[226:229], v[158:159], off offset:512
	global_load_dwordx4 v[230:233], v[158:159], off offset:576
	s_waitcnt vmcnt(8)
	v_pk_mul_f32 v[234:235], v[234:235], s[20:21] op_sel_hi:[1,0]
	v_pk_mul_f32 v[236:237], v[236:237], s[20:21] op_sel_hi:[1,0]
	v_pk_mul_f32 v[238:239], v[238:239], s[20:21] op_sel_hi:[1,0]
	v_pk_mul_f32 v[240:241], v[240:241], s[20:21] op_sel_hi:[1,0]
	v_pk_mul_f32 v[242:243], v[242:243], s[20:21] op_sel_hi:[1,0]
	v_pk_mul_f32 v[244:245], v[244:245], s[20:21] op_sel_hi:[1,0]
	v_pk_mul_f32 v[246:247], v[246:247], s[20:21] op_sel_hi:[1,0]
	v_pk_mul_f32 v[248:249], v[248:249], s[20:21] op_sel_hi:[1,0]
	v_pk_fma_f32 v[92:93], v[92:93], v[136:137], v[234:235]
	v_pk_fma_f32 v[94:95], v[94:95], v[138:139], v[236:237]
	v_pk_fma_f32 v[88:89], v[88:89], v[140:141], v[238:239]
	v_pk_fma_f32 v[90:91], v[90:91], v[142:143], v[240:241]
	v_pk_fma_f32 v[84:85], v[84:85], v[132:133], v[242:243]
	v_pk_fma_f32 v[86:87], v[86:87], v[134:135], v[244:245]
	v_pk_fma_f32 v[80:81], v[80:81], v[128:129], v[246:247]
	v_pk_fma_f32 v[82:83], v[82:83], v[130:131], v[248:249]
	v_add_co_u32_e32 v158, vcc, 0x240000, v156
	s_nop 1
	v_addc_co_u32_e32 v159, vcc, 0, v157, vcc
	global_load_dwordx4 v[234:237], v[158:159], off
	global_load_dwordx4 v[238:241], v[158:159], off offset:64
	global_load_dwordx4 v[242:245], v[158:159], off offset:512
	global_load_dwordx4 v[246:249], v[158:159], off offset:576
	s_waitcnt vmcnt(8)
	v_pk_mul_f32 v[174:175], v[174:175], s[20:21] op_sel_hi:[1,0]
	v_pk_mul_f32 v[176:177], v[176:177], s[20:21] op_sel_hi:[1,0]
	v_pk_mul_f32 v[178:179], v[178:179], s[20:21] op_sel_hi:[1,0]
	v_pk_mul_f32 v[180:181], v[180:181], s[20:21] op_sel_hi:[1,0]
	v_pk_mul_f32 v[182:183], v[182:183], s[20:21] op_sel_hi:[1,0]
	v_pk_mul_f32 v[184:185], v[184:185], s[20:21] op_sel_hi:[1,0]
	v_pk_mul_f32 v[186:187], v[186:187], s[20:21] op_sel_hi:[1,0]
	v_pk_mul_f32 v[188:189], v[188:189], s[20:21] op_sel_hi:[1,0]
	v_pk_fma_f32 v[76:77], v[76:77], v[136:137], v[174:175]
	v_pk_fma_f32 v[78:79], v[78:79], v[138:139], v[176:177]
	v_pk_fma_f32 v[72:73], v[72:73], v[140:141], v[178:179]
	v_pk_fma_f32 v[74:75], v[74:75], v[142:143], v[180:181]
	v_pk_fma_f32 v[68:69], v[68:69], v[132:133], v[182:183]
	v_pk_fma_f32 v[70:71], v[70:71], v[134:135], v[184:185]
	v_pk_fma_f32 v[64:65], v[64:65], v[128:129], v[186:187]
	v_pk_fma_f32 v[66:67], v[66:67], v[130:131], v[188:189]
	v_add_co_u32_e32 v158, vcc, 0x280000, v156
	s_nop 1
	v_addc_co_u32_e32 v159, vcc, 0, v157, vcc
	global_load_dwordx4 v[174:177], v[158:159], off
	global_load_dwordx4 v[178:181], v[158:159], off offset:64
	global_load_dwordx4 v[182:185], v[158:159], off offset:512
	global_load_dwordx4 v[186:189], v[158:159], off offset:576
	s_waitcnt vmcnt(8)
	v_pk_mul_f32 v[218:219], v[218:219], s[20:21] op_sel_hi:[1,0]
	v_pk_mul_f32 v[220:221], v[220:221], s[20:21] op_sel_hi:[1,0]
	v_pk_mul_f32 v[222:223], v[222:223], s[20:21] op_sel_hi:[1,0]
	v_pk_mul_f32 v[224:225], v[224:225], s[20:21] op_sel_hi:[1,0]
	v_pk_mul_f32 v[226:227], v[226:227], s[20:21] op_sel_hi:[1,0]
	v_pk_mul_f32 v[228:229], v[228:229], s[20:21] op_sel_hi:[1,0]
	v_pk_mul_f32 v[230:231], v[230:231], s[20:21] op_sel_hi:[1,0]
	v_pk_mul_f32 v[232:233], v[232:233], s[20:21] op_sel_hi:[1,0]
	v_pk_fma_f32 v[60:61], v[60:61], v[136:137], v[218:219]
	v_pk_fma_f32 v[62:63], v[62:63], v[138:139], v[220:221]
	v_pk_fma_f32 v[56:57], v[56:57], v[140:141], v[222:223]
	v_pk_fma_f32 v[58:59], v[58:59], v[142:143], v[224:225]
	v_pk_fma_f32 v[52:53], v[52:53], v[132:133], v[226:227]
	v_pk_fma_f32 v[54:55], v[54:55], v[134:135], v[228:229]
	v_pk_fma_f32 v[48:49], v[48:49], v[128:129], v[230:231]
	v_pk_fma_f32 v[50:51], v[50:51], v[130:131], v[232:233]
	v_add_co_u32_e32 v158, vcc, 0x2c0000, v156
	s_nop 1
	v_addc_co_u32_e32 v159, vcc, 0, v157, vcc
	global_load_dwordx4 v[218:221], v[158:159], off
	global_load_dwordx4 v[222:225], v[158:159], off offset:64
	global_load_dwordx4 v[226:229], v[158:159], off offset:512
	global_load_dwordx4 v[230:233], v[158:159], off offset:576
	s_waitcnt vmcnt(8)
; #define LAS __attribute__((address_space(3)))
;     DI bool operator()(f32x4 (&acc)[2][2][4][2], const pg8::Unit& u, int wr, int wc, int fr, int fq) const {
;     ...
;             for (int ai = 0; ai < 2; ++ai)
; #pragma unroll
;                 for (int m = 0; m < 4; ++m) { const char* xr = xt + (size_t)(ai * 128 + m * 16) * DM * 4;
; #pragma unroll
;                     for (int bj = 0; bj < 2; ++bj)
; #pragma unroll
;                         for (int n = 0; n < 2; ++n) { const f32x4 xv = *(const f32x4*)(xr + loff + (bj * 128 + n * 16) * 4); acc[ai][bj][m][n] = xv * ALPHA_F + gv[bj][n] * acc[ai][bj][m][n]; }
;                     asm volatile("" : "+v"(acc[ai][0][m][0]), "+v"(acc[ai][0][m][1]), "+v"(acc[ai][1][m][0]), "+v"(acc[ai][1][m][1]) :: "memory"); }
;         }
;         LAS f32x2v* Pt = (LAS f32x2v*)ptab;
; #pragma unroll
;         for (int ai = 0; ai < 2; ++ai)
; #pragma unroll
;             for (int m = 0; m < 4; ++m) { float s1 = 0.f, s2 = 0.f;
; #pragma unroll
;                 for (int bj = 0; bj < 2; ++bj)
; #pragma unroll
;                     for (int n = 0; n < 2; ++n) { const f32x4 v = acc[ai][bj][m][n]; s1 += (v[0] + v[1]) + (v[2] + v[3]); s2 += (v[0] * v[0] + v[1] * v[1]) + (v[2] * v[2] + v[3] * v[3]); }
;                 s1 += __shfl_xor(s1, 16); s1 += __shfl_xor(s1, 32); s2 += __shfl_xor(s2, 16); s2 += __shfl_xor(s2, 32);
;                 if (fq == 0) Pt[(ai * 128 + wr * 64 + m * 16 + fr) * 4 + wc] = (f32x2v){s1, s2}; }
	v_pk_mul_f32 v[234:235], v[234:235], s[20:21] op_sel_hi:[1,0]
	v_pk_mul_f32 v[236:237], v[236:237], s[20:21] op_sel_hi:[1,0]
	v_pk_mul_f32 v[238:239], v[238:239], s[20:21] op_sel_hi:[1,0]
	v_pk_mul_f32 v[240:241], v[240:241], s[20:21] op_sel_hi:[1,0]
	v_pk_mul_f32 v[242:243], v[242:243], s[20:21] op_sel_hi:[1,0]
	v_pk_mul_f32 v[244:245], v[244:245], s[20:21] op_sel_hi:[1,0]
	v_pk_mul_f32 v[246:247], v[246:247], s[20:21] op_sel_hi:[1,0]
	v_pk_mul_f32 v[248:249], v[248:249], s[20:21] op_sel_hi:[1,0]
	v_pk_fma_f32 v[44:45], v[44:45], v[136:137], v[234:235]
	v_pk_fma_f32 v[46:47], v[46:47], v[138:139], v[236:237]
	v_pk_fma_f32 v[40:41], v[40:41], v[140:141], v[238:239]
	v_pk_fma_f32 v[42:43], v[42:43], v[142:143], v[240:241]
	v_pk_fma_f32 v[36:37], v[36:37], v[132:133], v[242:243]
	v_pk_fma_f32 v[38:39], v[38:39], v[134:135], v[244:245]
	v_pk_fma_f32 v[32:33], v[32:33], v[128:129], v[246:247]
	v_pk_fma_f32 v[34:35], v[34:35], v[130:131], v[248:249]
	s_waitcnt vmcnt(4)
	v_pk_mul_f32 v[174:175], v[174:175], s[20:21] op_sel_hi:[1,0]
	v_pk_mul_f32 v[176:177], v[176:177], s[20:21] op_sel_hi:[1,0]
	v_pk_mul_f32 v[178:179], v[178:179], s[20:21] op_sel_hi:[1,0]
	v_pk_mul_f32 v[180:181], v[180:181], s[20:21] op_sel_hi:[1,0]
	v_pk_mul_f32 v[182:183], v[182:183], s[20:21] op_sel_hi:[1,0]
	v_pk_mul_f32 v[184:185], v[184:185], s[20:21] op_sel_hi:[1,0]
	v_pk_mul_f32 v[186:187], v[186:187], s[20:21] op_sel_hi:[1,0]
	v_pk_mul_f32 v[188:189], v[188:189], s[20:21] op_sel_hi:[1,0]
	v_pk_fma_f32 v[28:29], v[28:29], v[136:137], v[174:175]
	v_pk_fma_f32 v[30:31], v[30:31], v[138:139], v[176:177]
	v_pk_fma_f32 v[20:21], v[20:21], v[140:141], v[178:179]
	v_pk_fma_f32 v[22:23], v[22:23], v[142:143], v[180:181]
	v_pk_fma_f32 v[12:13], v[12:13], v[132:133], v[182:183]
	v_pk_fma_f32 v[14:15], v[14:15], v[134:135], v[184:185]
	v_pk_fma_f32 v[4:5], v[4:5], v[128:129], v[186:187]
	v_pk_fma_f32 v[6:7], v[6:7], v[130:131], v[188:189]
	s_waitcnt vmcnt(0)
	v_pk_mul_f32 v[218:219], v[218:219], s[20:21] op_sel_hi:[1,0]
	v_pk_mul_f32 v[220:221], v[220:221], s[20:21] op_sel_hi:[1,0]
	v_pk_mul_f32 v[222:223], v[222:223], s[20:21] op_sel_hi:[1,0]
	v_pk_mul_f32 v[224:225], v[224:225], s[20:21] op_sel_hi:[1,0]
	v_pk_mul_f32 v[226:227], v[226:227], s[20:21] op_sel_hi:[1,0]
	v_pk_mul_f32 v[228:229], v[228:229], s[20:21] op_sel_hi:[1,0]
	v_pk_mul_f32 v[230:231], v[230:231], s[20:21] op_sel_hi:[1,0]
	v_pk_mul_f32 v[232:233], v[232:233], s[20:21] op_sel_hi:[1,0]
	v_pk_fma_f32 v[24:25], v[24:25], v[136:137], v[218:219]
	v_pk_fma_f32 v[26:27], v[26:27], v[138:139], v[220:221]
	v_pk_fma_f32 v[16:17], v[16:17], v[140:141], v[222:223]
	v_pk_fma_f32 v[18:19], v[18:19], v[142:143], v[224:225]
	v_pk_fma_f32 v[8:9], v[8:9], v[132:133], v[226:227]
	v_pk_fma_f32 v[10:11], v[10:11], v[134:135], v[228:229]
	v_pk_fma_f32 v[0:1], v[0:1], v[128:129], v[230:231]
	v_pk_fma_f32 v[2:3], v[2:3], v[130:131], v[232:233]
	v_mul_f32_e32 v200, v122, v122
	v_mul_f32_e32 v191, v124, v124
	v_mul_f32_e32 v193, v125, v125
	v_mul_f32_e32 v195, v126, v126
	v_mul_f32_e32 v199, v127, v127
	v_mov_b32_e32 v190, v120
	v_mov_b32_e32 v192, v121
	v_mov_b32_e32 v194, v122
	v_mov_b32_e32 v198, v123
	v_pk_fma_f32 v[200:201], v[122:123], v[122:123], v[200:201] op_sel_hi:[1,1,0]
	v_mul_f32_e32 v203, v116, v116
	v_mul_f32_e32 v205, v117, v117
	v_mul_f32_e32 v207, v118, v118
	v_mul_f32_e32 v209, v119, v119
	v_mov_b32_e32 v202, v116
	v_mov_b32_e32 v204, v117
	v_mov_b32_e32 v206, v118
	v_mov_b32_e32 v208, v119
	v_pk_add_f32 v[190:191], v[190:191], v[192:193]
	v_pk_add_f32 v[192:193], v[194:195], v[198:199]
	v_mov_b32_e32 v200, v149
	v_mul_f32_e32 v211, v112, v112
	v_mul_f32_e32 v213, v113, v113
	v_mul_f32_e32 v215, v114, v114
	v_mul_f32_e32 v217, v115, v115
	v_mov_b32_e32 v210, v112
	v_mov_b32_e32 v212, v113
	v_mov_b32_e32 v214, v114
	v_mov_b32_e32 v216, v115
	v_pk_add_f32 v[194:195], v[206:207], v[208:209]
	v_pk_add_f32 v[190:191], v[190:191], v[192:193]
	v_pk_add_f32 v[198:199], v[210:211], v[212:213]
	v_and_b32_e32 v157, 64, v164
	v_xor_b32_e32 v156, 16, v164
	v_add_u32_e32 v167, 64, v157
	v_cmp_lt_i32_e32 vcc, v156, v167
	v_add_f32_e32 v158, v126, v127
	v_mul_f32_e32 v157, v120, v120
	v_cndmask_b32_e32 v156, v164, v156, vcc
	v_lshlrev_b32_e32 v166, 2, v156
	v_add_f32_e32 v156, v124, v125
	v_mul_f32_e32 v159, v121, v121
	v_pk_add_f32 v[156:157], v[156:157], v[158:159]
	v_pk_add_f32 v[158:159], v[202:203], v[204:205]
	v_pk_add_f32 v[156:157], v[156:157], v[200:201]
	v_pk_add_f32 v[202:203], v[214:215], v[216:217]
	v_pk_add_f32 v[158:159], v[158:159], v[194:195]
	v_pk_add_f32 v[156:157], v[190:191], v[156:157]
	v_pk_add_f32 v[192:193], v[198:199], v[202:203]
	v_pk_add_f32 v[156:157], v[158:159], v[156:157]
	v_xor_b32_e32 v190, 32, v164
	v_pk_add_f32 v[156:157], v[192:193], v[156:157]
	ds_bpermute_b32 v158, v166, v156
	ds_bpermute_b32 v159, v166, v157
	v_cmp_lt_i32_e32 vcc, v190, v167
	s_waitcnt lgkmcnt(0)
	v_pk_add_f32 v[156:157], v[156:157], v[158:159]
	v_cndmask_b32_e32 v167, v164, v190, vcc
	v_lshlrev_b32_e32 v167, 2, v167
	ds_bpermute_b32 v158, v167, v156
	ds_bpermute_b32 v159, v167, v157
	v_cmp_eq_u32_e32 vcc, 0, v168
	v_lshl_add_u32 v128, v173, 3, s68
	v_lshl_add_u32 v132, v169, 5, v128
	s_and_saveexec_b64 s[28:29], vcc
	s_cbranch_execz .LBB0_914
	s_waitcnt lgkmcnt(0)
	v_pk_add_f32 v[128:129], v[156:157], v[158:159]
	ds_write_b64 v132, v[128:129]
